# hgrn_out x4: scanned-state copy loads issued ~700 instructions before their LDS writes (private registers), removing one exposed round trip per unit
# speedup vs baseline: 1.0090x; 1.0062x over previous
.LBB0_1395:
	s_or_b64 exec, exec, s[6:7]
	s_load_dwordx2 s[16:17], s[62:63], 0xc0
	s_mov_b64 s[20:21], exec
	s_mov_b64 exec, -1
	v_readlane_b32 s18, v253, 21
	v_readlane_b32 s19, v253, 22
	v_lshlrev_b32_e32 v192, 4, v208
	v_and_b32_e32 v192, 0xf0, v192
	v_lshrrev_b32_e32 v193, 4, v208
	v_lshl_add_u32 v192, v193, 8, v192
	s_waitcnt lgkmcnt(0)
	s_add_u32 s16, s16, s18
	s_addc_u32 s17, s17, s19
	s_add_u32 s16, s16, 0x264c2800
	s_addc_u32 s17, s17, 0
	global_load_dwordx4 v[176:179], v192, s[16:17]
	s_add_u32 s16, s16, 0x2000
	s_addc_u32 s17, s17, 0
	global_load_dwordx4 v[180:183], v192, s[16:17]
	s_add_u32 s16, s16, 0x2000
	s_addc_u32 s17, s17, 0
	global_load_dwordx4 v[184:187], v192, s[16:17]
	s_add_u32 s16, s16, 0x2000
	s_addc_u32 s17, s17, 0
	global_load_dwordx4 v[188:191], v192, s[16:17]
	s_mov_b64 exec, s[20:21]
	v_mul_f32_e32 v1, 0x3fb8aa3b, v95
	v_exp_f32_e32 v1, v1
	v_lshlrev_b32_e32 v10, 16, v142
	v_and_b32_e32 v11, 0xffff0000, v142
	ds_read_b64 v[8:9], v9
	v_add_f32_e32 v1, 1.0, v1
	v_rcp_f32_e32 v6, v1
	v_mul_f32_e32 v1, 0x3fb8aa3b, v94
	v_exp_f32_e32 v1, v1
	s_nop 0
	v_add_f32_e32 v1, 1.0, v1
	v_rcp_f32_e32 v7, v1
	v_mul_f32_e32 v1, 0xbfb8aa3b, v10
	v_exp_f32_e32 v1, v1
	v_pk_mul_f32 v[6:7], v[4:5], v[6:7]
	v_add_f32_e32 v1, 1.0, v1
	v_rcp_f32_e32 v12, v1
	v_mul_f32_e32 v1, 0xbfb8aa3b, v11
	v_exp_f32_e32 v1, v1
	s_nop 0
	v_add_f32_e32 v1, 1.0, v1
	v_rcp_f32_e32 v13, v1
	s_nop 0
	v_pk_mul_f32 v[10:11], v[12:13], v[10:11]
	s_waitcnt lgkmcnt(0)
	v_exp_f32_e32 v12, v8
	v_exp_f32_e32 v13, v9
	v_pk_mul_f32 v[10:11], v[10:11], s[0:1] op_sel_hi:[1,0]
	s_nop 0
	v_pk_mul_f32 v[12:13], v[10:11], v[12:13]
	s_nop 0
	v_cvt_pk_bf16_f32 v1, v12, v13
	v_add_f32_e32 v12, v3, v8
	v_add_f32_e32 v13, v53, v9
	v_exp_f32_e32 v12, v12
	v_exp_f32_e32 v13, v13
	s_nop 0
	v_pk_mul_f32 v[10:11], v[10:11], v[12:13]
	s_nop 0
	v_cvt_pk_bf16_f32 v10, v10, v11
	v_add_u32_e32 v11, 16, v0
	ds_write2st64_b32 v11, v1, v10 offset0:137 offset1:205
	s_and_saveexec_b64 s[6:7], vcc
	s_cbranch_execz .LBB0_1399
	v_sub_f32_e64 v1, -v3, v8
	v_min_f32_e32 v1, 0x42c80000, v1
	v_exp_f32_e32 v10, v1
	v_sub_f32_e64 v1, -v53, v9
	v_min_f32_e32 v1, 0x42c80000, v1
	v_exp_f32_e32 v11, v1
	s_nop 0
	v_pk_mul_f32 v[10:11], v[6:7], v[10:11]
	s_nop 0
	v_cvt_pk_bf16_f32 v1, v10, v11
	v_mad_u64_u32 v[10:11], s[14:15], v31, s50, v[2:3]
	ds_write_b32 v10, v1
	s_or_b64 exec, exec, s[6:7]
	s_and_saveexec_b64 s[6:7], s[8:9]
	s_cbranch_execnz .LBB0_1400

.LBB0_1443:
	s_or_b64 exec, exec, s[6:7]
	v_readlane_b32 s2, v253, 21
	v_readlane_b32 s3, v253, 22
	v_lshlrev_b32_e32 v2, 4, v43
	v_and_b32_e32 v166, 0xf0, v2
	s_waitcnt vmcnt(0)
	v_lshl_add_u64 v[0:1], v[16:17], 0, s[2:3]
	v_lshl_add_u64 v[0:1], v[0:1], 0, v[166:167]
	s_mov_b64 s[2:3], 0x264c2800
	v_ashrrev_i32_e32 v7, 4, v43
	v_lshl_add_u64 v[4:5], v[0:1], 0, s[2:3]
	v_lshlrev_b32_e32 v0, 7, v7
	v_ashrrev_i32_e32 v1, 31, v0
	v_lshl_add_u64 v[0:1], v[0:1], 1, v[4:5]
	s_waitcnt lgkmcnt(0)
	s_barrier
	v_add_u32_e32 v6, 0, v166
	v_mad_u64_u32 v[100:101], s[6:7], v7, s50, v[6:7]
	v_lshlrev_b32_e32 v11, 4, v22
	v_readlane_b32 s2, v254, 45
	v_add_u32_e32 v0, 0x200, v43
	v_ashrrev_i32_e32 v7, 4, v0
	v_lshlrev_b32_e32 v0, 7, v7
	v_ashrrev_i32_e32 v1, 31, v0
	v_lshl_add_u64 v[0:1], v[0:1], 1, v[4:5]
	v_mad_u64_u32 v[102:103], s[6:7], v7, s50, v[6:7]
	v_add_u32_e32 v0, 0x400, v43
	v_ashrrev_i32_e32 v7, 4, v0
	v_lshlrev_b32_e32 v0, 7, v7
	v_ashrrev_i32_e32 v1, 31, v0
	v_lshl_add_u64 v[0:1], v[0:1], 1, v[4:5]
	v_mad_u64_u32 v[104:105], s[6:7], v7, s50, v[6:7]
	v_add_u32_e32 v0, 0x600, v43
	v_ashrrev_i32_e32 v7, 4, v0
	v_lshlrev_b32_e32 v0, 7, v7
	v_ashrrev_i32_e32 v1, 31, v0
	v_lshl_add_u64 v[0:1], v[0:1], 1, v[4:5]
	v_mad_u64_u32 v[4:5], s[6:7], v7, s50, v[6:7]
	v_and_b32_e32 v7, 15, v43
	v_mov_b32_e32 v5, 0
	ds_write_b128 v100, v[176:179]
	ds_write_b128 v102, v[180:183]
	ds_write_b128 v104, v[184:187]
	ds_write_b128 v4, v[188:191]
	v_lshlrev_b32_e32 v0, 1, v40
	v_and_b32_e32 v1, 2, v0
	v_mad_u64_u32 v[2:3], s[6:7], v22, v22, v[22:23]
	v_or_b32_e32 v0, v11, v7
	v_mul_lo_u32 v0, v0, s50
	v_and_b32_e32 v3, 48, v45
	v_add3_u32 v8, 0, v0, v3
	v_lshl_add_u32 v9, v2, 3, v7
	v_add_u32_e32 v6, s2, v3
	v_cmp_gt_i32_e32 vcc, v1, v22
	v_cmp_le_i32_e64 s[8:9], v1, v22
	v_lshlrev_b32_e32 v10, 4, v1
	v_mov_b32_e32 v0, 0
	v_mov_b32_e32 v2, 0
	v_mov_b32_e32 v3, 0
	v_mov_b32_e32 v4, 0
	s_and_saveexec_b64 s[6:7], s[8:9]
	s_cbranch_execz .LBB0_1445
	v_add_u32_e32 v2, v9, v10
	v_mad_u64_u32 v[60:61], s[8:9], v2, s50, v[6:7]
	ds_read_b128 v[2:5], v8 offset:34816
	ds_read_b128 v[12:15], v60
	s_waitcnt lgkmcnt(0)
	v_mfma_f32_16x16x32_bf16 v[2:5], v[2:5], v[12:15], 0
	ds_read_b128 v[12:15], v8 offset:34880
	ds_read_b128 v[56:59], v60 offset:64
	s_waitcnt lgkmcnt(0)
	v_mfma_f32_16x16x32_bf16 v[2:5], v[12:15], v[56:59], v[2:5]
	ds_read_b128 v[12:15], v8 offset:34944
	ds_read_b128 v[56:59], v60 offset:128
	s_waitcnt lgkmcnt(0)
	v_mfma_f32_16x16x32_bf16 v[2:5], v[12:15], v[56:59], v[2:5]
	ds_read_b128 v[12:15], v8 offset:35008
	ds_read_b128 v[56:59], v60 offset:192
	s_waitcnt lgkmcnt(0)
	v_mfma_f32_16x16x32_bf16 v[2:5], v[12:15], v[56:59], v[2:5]

.LBB0_1463:
	s_or_b64 exec, exec, s[6:7]
	s_load_dwordx2 s[16:17], s[62:63], 0xc0
	s_mov_b64 s[20:21], exec
	s_mov_b64 exec, -1
	v_readlane_b32 s18, v253, 26
	v_readlane_b32 s19, v253, 27
	v_lshlrev_b32_e32 v192, 4, v208
	v_and_b32_e32 v192, 0xf0, v192
	v_lshrrev_b32_e32 v193, 4, v208
	v_lshl_add_u32 v192, v193, 8, v192
	s_waitcnt lgkmcnt(0)
	s_add_u32 s16, s16, s18
	s_addc_u32 s17, s17, s19
	s_add_u32 s16, s16, 0x264c2800
	s_addc_u32 s17, s17, 0
	global_load_dwordx4 v[176:179], v192, s[16:17]
	s_add_u32 s16, s16, 0x2000
	s_addc_u32 s17, s17, 0
	global_load_dwordx4 v[180:183], v192, s[16:17]
	s_add_u32 s16, s16, 0x2000
	s_addc_u32 s17, s17, 0
	global_load_dwordx4 v[184:187], v192, s[16:17]
	s_add_u32 s16, s16, 0x2000
	s_addc_u32 s17, s17, 0
	global_load_dwordx4 v[188:191], v192, s[16:17]
	s_mov_b64 exec, s[20:21]
	v_mul_f32_e32 v1, 0x3fb8aa3b, v108
	v_exp_f32_e32 v1, v1
	v_lshlrev_b32_e32 v8, 16, v54
	v_and_b32_e32 v9, 0xffff0000, v54
	v_add_u32_e32 v13, 16, v0
	v_add_f32_e32 v1, 1.0, v1
	v_rcp_f32_e32 v6, v1
	v_mul_f32_e32 v1, 0x3fb8aa3b, v107
	v_exp_f32_e32 v1, v1
	s_nop 0
	v_add_f32_e32 v1, 1.0, v1
	v_rcp_f32_e32 v7, v1
	v_mul_f32_e32 v1, 0xbfb8aa3b, v8
	v_exp_f32_e32 v1, v1
	v_pk_mul_f32 v[6:7], v[4:5], v[6:7]
	v_add_f32_e32 v1, 1.0, v1
	v_rcp_f32_e32 v14, v1
	v_mul_f32_e32 v1, 0xbfb8aa3b, v9
	v_exp_f32_e32 v1, v1
	s_nop 0
	v_add_f32_e32 v1, 1.0, v1
	v_rcp_f32_e32 v15, v1
	s_nop 0
	v_pk_mul_f32 v[8:9], v[14:15], v[8:9]
	s_nop 0
	v_pk_mul_f32 v[14:15], v[8:9], s[0:1] op_sel_hi:[1,0]
	ds_read_b64 v[8:9], v106
	s_waitcnt lgkmcnt(0)
	v_exp_f32_e32 v54, v8
	v_exp_f32_e32 v55, v9
	v_add_f32_e32 v10, v3, v8
	v_pk_mul_f32 v[54:55], v[14:15], v[54:55]
	s_nop 0
	v_cvt_pk_bf16_f32 v1, v54, v55
	v_exp_f32_e32 v54, v10
	v_add_f32_e32 v10, v19, v9
	v_exp_f32_e32 v55, v10
	s_nop 0
	v_pk_mul_f32 v[14:15], v[14:15], v[54:55]
	s_nop 0
	v_cvt_pk_bf16_f32 v10, v14, v15
	ds_write2st64_b32 v13, v1, v10 offset0:137 offset1:205
	s_and_saveexec_b64 s[6:7], vcc
	s_cbranch_execz .LBB0_1467
	v_sub_f32_e64 v1, -v3, v8
	v_min_f32_e32 v1, 0x42c80000, v1
	v_exp_f32_e32 v14, v1
	v_sub_f32_e64 v1, -v19, v9
	v_min_f32_e32 v1, 0x42c80000, v1
	v_exp_f32_e32 v15, v1
	s_nop 0
	v_pk_mul_f32 v[14:15], v[6:7], v[14:15]
	s_nop 0
	v_cvt_pk_bf16_f32 v1, v14, v15
	v_mad_u64_u32 v[14:15], s[14:15], v72, s50, v[2:3]
	ds_write_b32 v14, v1
	s_or_b64 exec, exec, s[6:7]
	s_and_saveexec_b64 s[6:7], s[8:9]
	s_cbranch_execnz .LBB0_1468

.LBB0_1511:
	s_or_b64 exec, exec, s[6:7]
	v_readlane_b32 s2, v253, 26
	v_readlane_b32 s3, v253, 27
	v_lshlrev_b32_e32 v2, 4, v97
	v_and_b32_e32 v166, 0xf0, v2
	s_waitcnt vmcnt(0)
	v_lshl_add_u64 v[0:1], v[20:21], 0, s[2:3]
	v_lshl_add_u64 v[0:1], v[0:1], 0, v[166:167]
	s_mov_b64 s[2:3], 0x264c2800
	v_ashrrev_i32_e32 v7, 4, v97
	v_lshl_add_u64 v[4:5], v[0:1], 0, s[2:3]
	v_lshlrev_b32_e32 v0, 7, v7
	v_ashrrev_i32_e32 v1, 31, v0
	v_lshl_add_u64 v[0:1], v[0:1], 1, v[4:5]
	s_waitcnt lgkmcnt(0)
	s_barrier
	v_add_u32_e32 v6, 0, v166
	v_mad_u64_u32 v[136:137], s[6:7], v7, s50, v[6:7]
	v_lshlrev_b32_e32 v12, 4, v18
	v_readlane_b32 s2, v254, 45
	v_add_u32_e32 v0, 0x200, v97
	v_ashrrev_i32_e32 v7, 4, v0
	v_lshlrev_b32_e32 v0, 7, v7
	v_ashrrev_i32_e32 v1, 31, v0
	v_lshl_add_u64 v[0:1], v[0:1], 1, v[4:5]
	v_mad_u64_u32 v[138:139], s[6:7], v7, s50, v[6:7]
	v_add_u32_e32 v0, 0x400, v97
	v_ashrrev_i32_e32 v7, 4, v0
	v_lshlrev_b32_e32 v0, 7, v7
	v_ashrrev_i32_e32 v1, 31, v0
	v_lshl_add_u64 v[0:1], v[0:1], 1, v[4:5]
	v_mad_u64_u32 v[140:141], s[6:7], v7, s50, v[6:7]
	v_add_u32_e32 v0, 0x600, v97
	v_ashrrev_i32_e32 v7, 4, v0
	v_lshlrev_b32_e32 v0, 7, v7
	v_ashrrev_i32_e32 v1, 31, v0
	v_lshl_add_u64 v[0:1], v[0:1], 1, v[4:5]
	v_mad_u64_u32 v[4:5], s[6:7], v7, s50, v[6:7]
	v_and_b32_e32 v7, 15, v97
	v_mov_b32_e32 v5, 0
	ds_write_b128 v136, v[176:179]
	ds_write_b128 v138, v[180:183]
	ds_write_b128 v140, v[184:187]
	ds_write_b128 v4, v[188:191]
	v_lshlrev_b32_e32 v0, 1, v95
	v_and_b32_e32 v1, 2, v0
	v_mad_u64_u32 v[2:3], s[6:7], v18, v18, v[18:19]
	v_or_b32_e32 v0, v12, v7
	v_mul_lo_u32 v0, v0, s50
	v_and_b32_e32 v3, 48, v11
	v_add3_u32 v8, 0, v0, v3
	v_lshl_add_u32 v9, v2, 3, v7
	v_add_u32_e32 v6, s2, v3
	v_cmp_gt_i32_e32 vcc, v1, v18
	v_cmp_le_i32_e64 s[8:9], v1, v18
	v_lshlrev_b32_e32 v10, 4, v1
	v_mov_b32_e32 v0, 0
	v_mov_b32_e32 v2, 0
	v_mov_b32_e32 v3, 0
	v_mov_b32_e32 v4, 0
	s_and_saveexec_b64 s[6:7], s[8:9]
	s_cbranch_execz .LBB0_1513
	v_add_u32_e32 v2, v9, v10
	v_mad_u64_u32 v[14:15], s[8:9], v2, s50, v[6:7]
	ds_read_b128 v[2:5], v8 offset:34816
	ds_read_b128 v[98:101], v14
	s_waitcnt lgkmcnt(0)
	v_mfma_f32_16x16x32_bf16 v[2:5], v[2:5], v[98:101], 0
	ds_read_b128 v[98:101], v8 offset:34880
	ds_read_b128 v[102:105], v14 offset:64
	s_waitcnt lgkmcnt(0)
	v_mfma_f32_16x16x32_bf16 v[2:5], v[98:101], v[102:105], v[2:5]
	ds_read_b128 v[98:101], v8 offset:34944
	ds_read_b128 v[102:105], v14 offset:128
	s_waitcnt lgkmcnt(0)
	v_mfma_f32_16x16x32_bf16 v[2:5], v[98:101], v[102:105], v[2:5]
	ds_read_b128 v[98:101], v8 offset:35008
	ds_read_b128 v[102:105], v14 offset:192
	s_waitcnt lgkmcnt(0)
	v_mfma_f32_16x16x32_bf16 v[2:5], v[98:101], v[102:105], v[2:5]

.LBB0_1531:
	s_or_b64 exec, exec, s[6:7]
	s_load_dwordx2 s[16:17], s[62:63], 0xc0
	s_mov_b64 s[20:21], exec
	s_mov_b64 exec, -1
	v_readlane_b32 s18, v253, 31
	v_readlane_b32 s19, v253, 32
	v_lshlrev_b32_e32 v192, 4, v208
	v_and_b32_e32 v192, 0xf0, v192
	v_lshrrev_b32_e32 v193, 4, v208
	v_lshl_add_u32 v192, v193, 8, v192
	s_waitcnt lgkmcnt(0)
	s_add_u32 s16, s16, s18
	s_addc_u32 s17, s17, s19
	s_add_u32 s16, s16, 0x264c2800
	s_addc_u32 s17, s17, 0
	global_load_dwordx4 v[176:179], v192, s[16:17]
	s_add_u32 s16, s16, 0x2000
	s_addc_u32 s17, s17, 0
	global_load_dwordx4 v[180:183], v192, s[16:17]
	s_add_u32 s16, s16, 0x2000
	s_addc_u32 s17, s17, 0
	global_load_dwordx4 v[184:187], v192, s[16:17]
	s_add_u32 s16, s16, 0x2000
	s_addc_u32 s17, s17, 0
	global_load_dwordx4 v[188:191], v192, s[16:17]
	s_mov_b64 exec, s[20:21]
	v_mul_f32_e32 v1, 0x3fb8aa3b, v108
	v_exp_f32_e32 v1, v1
	v_lshlrev_b32_e32 v8, 16, v51
	v_and_b32_e32 v9, 0xffff0000, v51
	v_add_u32_e32 v13, 16, v0
	v_add_f32_e32 v1, 1.0, v1
	v_rcp_f32_e32 v6, v1
	v_mul_f32_e32 v1, 0x3fb8aa3b, v107
	v_exp_f32_e32 v1, v1
	s_nop 0
	v_add_f32_e32 v1, 1.0, v1
	v_rcp_f32_e32 v7, v1
	v_mul_f32_e32 v1, 0xbfb8aa3b, v8
	v_exp_f32_e32 v1, v1
	v_pk_mul_f32 v[6:7], v[4:5], v[6:7]
	v_add_f32_e32 v1, 1.0, v1
	v_rcp_f32_e32 v14, v1
	v_mul_f32_e32 v1, 0xbfb8aa3b, v9
	v_exp_f32_e32 v1, v1
	s_nop 0
	v_add_f32_e32 v1, 1.0, v1
	v_rcp_f32_e32 v15, v1
	s_nop 0
	v_pk_mul_f32 v[8:9], v[14:15], v[8:9]
	s_nop 0
	v_pk_mul_f32 v[14:15], v[8:9], s[0:1] op_sel_hi:[1,0]
	ds_read_b64 v[8:9], v106
	s_waitcnt lgkmcnt(0)
	v_exp_f32_e32 v106, v8
	v_exp_f32_e32 v107, v9
	v_add_f32_e32 v10, v3, v8
	v_pk_mul_f32 v[106:107], v[14:15], v[106:107]
	s_nop 0
	v_cvt_pk_bf16_f32 v1, v106, v107
	v_exp_f32_e32 v106, v10
	v_add_f32_e32 v10, v17, v9
	v_exp_f32_e32 v107, v10
	s_nop 0
	v_pk_mul_f32 v[14:15], v[14:15], v[106:107]
	s_nop 0
	v_cvt_pk_bf16_f32 v10, v14, v15
	ds_write2st64_b32 v13, v1, v10 offset0:137 offset1:205
	s_and_saveexec_b64 s[6:7], vcc
	s_cbranch_execz .LBB0_1535
	v_sub_f32_e64 v1, -v3, v8
	v_min_f32_e32 v1, 0x42c80000, v1
	v_exp_f32_e32 v14, v1
	v_sub_f32_e64 v1, -v17, v9
	v_min_f32_e32 v1, 0x42c80000, v1
	v_exp_f32_e32 v15, v1
	s_nop 0
	v_pk_mul_f32 v[14:15], v[6:7], v[14:15]
	s_nop 0
	v_cvt_pk_bf16_f32 v1, v14, v15
	v_mad_u64_u32 v[14:15], s[14:15], v77, s50, v[2:3]
	ds_write_b32 v14, v1
	s_or_b64 exec, exec, s[6:7]
	s_and_saveexec_b64 s[6:7], s[8:9]
	s_cbranch_execnz .LBB0_1536

.LBB0_1579:
	s_or_b64 exec, exec, s[6:7]
	v_readlane_b32 s2, v253, 31
	v_readlane_b32 s3, v253, 32
	v_lshlrev_b32_e32 v2, 4, v97
	v_and_b32_e32 v166, 0xf0, v2
	s_waitcnt vmcnt(0)
	v_lshl_add_u64 v[0:1], v[20:21], 0, s[2:3]
	v_lshl_add_u64 v[0:1], v[0:1], 0, v[166:167]
	s_mov_b64 s[2:3], 0x264c2800
	v_ashrrev_i32_e32 v7, 4, v97
	v_lshl_add_u64 v[4:5], v[0:1], 0, s[2:3]
	v_lshlrev_b32_e32 v0, 7, v7
	v_ashrrev_i32_e32 v1, 31, v0
	v_lshl_add_u64 v[0:1], v[0:1], 1, v[4:5]
	s_waitcnt lgkmcnt(0)
	s_barrier
	v_add_u32_e32 v6, 0, v166
	v_mad_u64_u32 v[136:137], s[6:7], v7, s50, v[6:7]
	v_lshlrev_b32_e32 v12, 4, v16
	v_readlane_b32 s2, v254, 45
	v_add_u32_e32 v0, 0x200, v97
	v_ashrrev_i32_e32 v7, 4, v0
	v_lshlrev_b32_e32 v0, 7, v7
	v_ashrrev_i32_e32 v1, 31, v0
	v_lshl_add_u64 v[0:1], v[0:1], 1, v[4:5]
	v_mad_u64_u32 v[138:139], s[6:7], v7, s50, v[6:7]
	v_add_u32_e32 v0, 0x400, v97
	v_ashrrev_i32_e32 v7, 4, v0
	v_lshlrev_b32_e32 v0, 7, v7
	v_ashrrev_i32_e32 v1, 31, v0
	v_lshl_add_u64 v[0:1], v[0:1], 1, v[4:5]
	v_mad_u64_u32 v[140:141], s[6:7], v7, s50, v[6:7]
	v_add_u32_e32 v0, 0x600, v97
	v_ashrrev_i32_e32 v7, 4, v0
	v_lshlrev_b32_e32 v0, 7, v7
	v_ashrrev_i32_e32 v1, 31, v0
	v_lshl_add_u64 v[0:1], v[0:1], 1, v[4:5]
	v_mad_u64_u32 v[4:5], s[6:7], v7, s50, v[6:7]
	v_and_b32_e32 v7, 15, v97
	v_mov_b32_e32 v5, 0
	ds_write_b128 v136, v[176:179]
	ds_write_b128 v138, v[180:183]
	ds_write_b128 v140, v[184:187]
	ds_write_b128 v4, v[188:191]
	v_lshlrev_b32_e32 v0, 1, v95
	v_and_b32_e32 v1, 2, v0
	v_mad_u64_u32 v[2:3], s[6:7], v16, v16, v[16:17]
	v_or_b32_e32 v0, v12, v7
	v_mul_lo_u32 v0, v0, s50
	v_and_b32_e32 v3, 48, v11
	v_add3_u32 v8, 0, v0, v3
	v_lshl_add_u32 v9, v2, 3, v7
	v_add_u32_e32 v6, s2, v3
	v_cmp_gt_i32_e32 vcc, v1, v16
	v_cmp_le_i32_e64 s[8:9], v1, v16
	v_lshlrev_b32_e32 v10, 4, v1
	v_mov_b32_e32 v0, 0
	v_mov_b32_e32 v2, 0
	v_mov_b32_e32 v3, 0
	v_mov_b32_e32 v4, 0
	s_and_saveexec_b64 s[6:7], s[8:9]
	s_cbranch_execz .LBB0_1581
	v_add_u32_e32 v2, v9, v10
	v_mad_u64_u32 v[14:15], s[8:9], v2, s50, v[6:7]
	ds_read_b128 v[2:5], v8 offset:34816
	ds_read_b128 v[98:101], v14
	s_waitcnt lgkmcnt(0)
	v_mfma_f32_16x16x32_bf16 v[2:5], v[2:5], v[98:101], 0
	ds_read_b128 v[98:101], v8 offset:34880
	ds_read_b128 v[102:105], v14 offset:64
	s_waitcnt lgkmcnt(0)
	v_mfma_f32_16x16x32_bf16 v[2:5], v[98:101], v[102:105], v[2:5]
	ds_read_b128 v[98:101], v8 offset:34944
	ds_read_b128 v[102:105], v14 offset:128
	s_waitcnt lgkmcnt(0)
	v_mfma_f32_16x16x32_bf16 v[2:5], v[98:101], v[102:105], v[2:5]
	ds_read_b128 v[98:101], v8 offset:35008
	ds_read_b128 v[102:105], v14 offset:192
	s_waitcnt lgkmcnt(0)
	v_mfma_f32_16x16x32_bf16 v[2:5], v[98:101], v[102:105], v[2:5]

.LBB0_1599:
	s_or_b64 exec, exec, s[6:7]
	s_load_dwordx2 s[16:17], s[62:63], 0xc0
	s_mov_b64 s[20:21], exec
	s_mov_b64 exec, -1
	v_readlane_b32 s18, v253, 34
	v_readlane_b32 s19, v253, 35
	v_lshlrev_b32_e32 v192, 4, v208
	v_and_b32_e32 v192, 0xf0, v192
	v_lshrrev_b32_e32 v193, 4, v208
	v_lshl_add_u32 v192, v193, 8, v192
	s_waitcnt lgkmcnt(0)
	s_add_u32 s16, s16, s18
	s_addc_u32 s17, s17, s19
	s_add_u32 s16, s16, 0x264c2800
	s_addc_u32 s17, s17, 0
	global_load_dwordx4 v[176:179], v192, s[16:17]
	s_add_u32 s16, s16, 0x2000
	s_addc_u32 s17, s17, 0
	global_load_dwordx4 v[180:183], v192, s[16:17]
	s_add_u32 s16, s16, 0x2000
	s_addc_u32 s17, s17, 0
	global_load_dwordx4 v[184:187], v192, s[16:17]
	s_add_u32 s16, s16, 0x2000
	s_addc_u32 s17, s17, 0
	global_load_dwordx4 v[188:191], v192, s[16:17]
	s_mov_b64 exec, s[20:21]
	v_mul_f32_e32 v1, 0x3fb8aa3b, v71
	v_exp_f32_e32 v1, v1
	v_lshlrev_b32_e32 v8, 16, v54
	v_and_b32_e32 v9, 0xffff0000, v54
	v_add_u32_e32 v13, 16, v0
	v_add_f32_e32 v1, 1.0, v1
	v_rcp_f32_e32 v6, v1
	v_mul_f32_e32 v1, 0x3fb8aa3b, v70
	v_exp_f32_e32 v1, v1
	s_nop 0
	v_add_f32_e32 v1, 1.0, v1
	v_rcp_f32_e32 v7, v1
	v_mul_f32_e32 v1, 0xbfb8aa3b, v8
	v_exp_f32_e32 v1, v1
	v_pk_mul_f32 v[6:7], v[4:5], v[6:7]
	v_add_f32_e32 v1, 1.0, v1
	v_rcp_f32_e32 v14, v1
	v_mul_f32_e32 v1, 0xbfb8aa3b, v9
	v_exp_f32_e32 v1, v1
	s_nop 0
	v_add_f32_e32 v1, 1.0, v1
	v_rcp_f32_e32 v15, v1
	s_nop 0
	v_pk_mul_f32 v[8:9], v[14:15], v[8:9]
	s_nop 0
	v_pk_mul_f32 v[14:15], v[8:9], s[0:1] op_sel_hi:[1,0]
	ds_read_b64 v[8:9], v69
	s_waitcnt lgkmcnt(0)
	v_exp_f32_e32 v54, v8
	v_exp_f32_e32 v55, v9
	v_add_f32_e32 v10, v3, v8
	v_pk_mul_f32 v[54:55], v[14:15], v[54:55]
	s_nop 0
	v_cvt_pk_bf16_f32 v1, v54, v55
	v_exp_f32_e32 v54, v10
	v_add_f32_e32 v10, v19, v9
	v_exp_f32_e32 v55, v10
	s_nop 0
	v_pk_mul_f32 v[14:15], v[14:15], v[54:55]
	s_nop 0
	v_cvt_pk_bf16_f32 v10, v14, v15
	ds_write2st64_b32 v13, v1, v10 offset0:137 offset1:205
	s_and_saveexec_b64 s[6:7], vcc
	s_cbranch_execz .LBB0_1603
	v_sub_f32_e64 v1, -v3, v8
	v_min_f32_e32 v1, 0x42c80000, v1
	v_exp_f32_e32 v14, v1
	v_sub_f32_e64 v1, -v19, v9
	v_min_f32_e32 v1, 0x42c80000, v1
	v_exp_f32_e32 v15, v1
	s_nop 0
	v_pk_mul_f32 v[14:15], v[6:7], v[14:15]
	s_nop 0
	v_cvt_pk_bf16_f32 v1, v14, v15
	v_mad_u64_u32 v[14:15], s[14:15], v25, s50, v[2:3]
	ds_write_b32 v14, v1
	s_or_b64 exec, exec, s[6:7]
	s_and_saveexec_b64 s[6:7], s[8:9]
	s_cbranch_execnz .LBB0_1604

.LBB0_1647:
	s_or_b64 exec, exec, s[6:7]
	v_readlane_b32 s2, v253, 34
	v_readlane_b32 s3, v253, 35
	v_lshlrev_b32_e32 v2, 4, v42
	v_and_b32_e32 v166, 0xf0, v2
	s_waitcnt vmcnt(0)
	v_lshl_add_u64 v[0:1], v[16:17], 0, s[2:3]
	v_lshl_add_u64 v[0:1], v[0:1], 0, v[166:167]
	s_mov_b64 s[2:3], 0x264c2800
	v_ashrrev_i32_e32 v7, 4, v42
	v_lshl_add_u64 v[4:5], v[0:1], 0, s[2:3]
	v_lshlrev_b32_e32 v0, 7, v7
	v_ashrrev_i32_e32 v1, 31, v0
	v_lshl_add_u64 v[0:1], v[0:1], 1, v[4:5]
	s_waitcnt lgkmcnt(0)
	s_barrier
	v_add_u32_e32 v6, 0, v166
	v_mad_u64_u32 v[132:133], s[6:7], v7, s50, v[6:7]
	v_lshlrev_b32_e32 v12, 4, v18
	v_readlane_b32 s2, v254, 45
	v_add_u32_e32 v0, 0x200, v42
	v_ashrrev_i32_e32 v7, 4, v0
	v_lshlrev_b32_e32 v0, 7, v7
	v_ashrrev_i32_e32 v1, 31, v0
	v_lshl_add_u64 v[0:1], v[0:1], 1, v[4:5]
	v_mad_u64_u32 v[134:135], s[6:7], v7, s50, v[6:7]
	v_add_u32_e32 v0, 0x400, v42
	v_ashrrev_i32_e32 v7, 4, v0
	v_lshlrev_b32_e32 v0, 7, v7
	v_ashrrev_i32_e32 v1, 31, v0
	v_lshl_add_u64 v[0:1], v[0:1], 1, v[4:5]
	v_mad_u64_u32 v[136:137], s[6:7], v7, s50, v[6:7]
	v_add_u32_e32 v0, 0x600, v42
	v_ashrrev_i32_e32 v7, 4, v0
	v_lshlrev_b32_e32 v0, 7, v7
	v_ashrrev_i32_e32 v1, 31, v0
	v_lshl_add_u64 v[0:1], v[0:1], 1, v[4:5]
	v_mad_u64_u32 v[4:5], s[6:7], v7, s50, v[6:7]
	v_and_b32_e32 v7, 15, v42
	v_mov_b32_e32 v5, 0
	ds_write_b128 v132, v[176:179]
	ds_write_b128 v134, v[180:183]
	ds_write_b128 v136, v[184:187]
	ds_write_b128 v4, v[188:191]
	v_lshlrev_b32_e32 v0, 1, v33
	v_and_b32_e32 v1, 2, v0
	v_mad_u64_u32 v[2:3], s[6:7], v18, v18, v[18:19]
	v_or_b32_e32 v0, v12, v7
	v_mul_lo_u32 v0, v0, s50
	v_and_b32_e32 v3, 48, v11
	v_add3_u32 v8, 0, v0, v3
	v_lshl_add_u32 v9, v2, 3, v7
	v_add_u32_e32 v6, s2, v3
	v_cmp_gt_i32_e32 vcc, v1, v18
	v_cmp_le_i32_e64 s[8:9], v1, v18
	v_lshlrev_b32_e32 v10, 4, v1
	v_mov_b32_e32 v0, 0
	v_mov_b32_e32 v2, 0
	v_mov_b32_e32 v3, 0
	v_mov_b32_e32 v4, 0
	s_and_saveexec_b64 s[6:7], s[8:9]
	s_cbranch_execz .LBB0_1649
	v_add_u32_e32 v2, v9, v10
	v_mad_u64_u32 v[14:15], s[8:9], v2, s50, v[6:7]
	ds_read_b128 v[2:5], v8 offset:34816
	ds_read_b128 v[44:47], v14
	s_waitcnt lgkmcnt(0)
	v_mfma_f32_16x16x32_bf16 v[2:5], v[2:5], v[44:47], 0
	ds_read_b128 v[44:47], v8 offset:34880
	ds_read_b128 v[48:51], v14 offset:64
	s_waitcnt lgkmcnt(0)
	v_mfma_f32_16x16x32_bf16 v[2:5], v[44:47], v[48:51], v[2:5]
	ds_read_b128 v[44:47], v8 offset:34944
	ds_read_b128 v[48:51], v14 offset:128
	s_waitcnt lgkmcnt(0)
	v_mfma_f32_16x16x32_bf16 v[2:5], v[44:47], v[48:51], v[2:5]
	ds_read_b128 v[44:47], v8 offset:35008
	ds_read_b128 v[48:51], v14 offset:192
	s_waitcnt lgkmcnt(0)
	v_mfma_f32_16x16x32_bf16 v[2:5], v[44:47], v[48:51], v[2:5]
